# SwiGLU epilogue with packed f32 ops and batched transcendentals (residual epilogues as compiled)
# baseline (speedup 1.0000x reference)
.LBB0_514:
	v_lshl_or_b32 v146, s58, 7, v142
	v_lshl_add_u32 v144, s59, 8, v140
	v_ashrrev_i32_e32 v147, 31, v146
	s_movk_i32 s30, 0x1600
	s_and_b64 vcc, exec, s[4:5]
	v_mov_b32_e32 v160, 0xbfb8aa3b
	v_mov_b32_e32 v161, 0xbfb8aa3b
	v_mov_b64_e32 v[164:165], s[20:21]
	v_lshlrev_b64 v[166:167], 1, v[146:147]
	v_pk_mul_f32 v[150:151], v[122:123], v[160:161]
	v_pk_mul_f32 v[152:153], v[124:125], v[160:161]
	v_pk_mul_f32 v[154:155], v[118:119], v[160:161]
	v_pk_mul_f32 v[156:157], v[120:121], v[160:161]
	v_exp_f32_e32 v150, v150
	v_exp_f32_e32 v151, v151
	v_exp_f32_e32 v152, v152
	v_exp_f32_e32 v153, v153
	v_exp_f32_e32 v154, v154
	v_exp_f32_e32 v155, v155
	v_exp_f32_e32 v156, v156
	v_exp_f32_e32 v157, v157
	v_pk_add_f32 v[150:151], v[150:151], 1.0 op_sel_hi:[1,0]
	v_pk_add_f32 v[152:153], v[152:153], 1.0 op_sel_hi:[1,0]
	v_pk_add_f32 v[154:155], v[154:155], 1.0 op_sel_hi:[1,0]
	v_pk_add_f32 v[156:157], v[156:157], 1.0 op_sel_hi:[1,0]
	v_rcp_f32_e32 v150, v150
	v_rcp_f32_e32 v151, v151
	v_rcp_f32_e32 v152, v152
	v_rcp_f32_e32 v153, v153
	v_rcp_f32_e32 v154, v154
	v_rcp_f32_e32 v155, v155
	v_rcp_f32_e32 v156, v156
	v_rcp_f32_e32 v157, v157
	v_pk_mul_f32 v[122:123], v[122:123], v[150:151]
	v_pk_mul_f32 v[124:125], v[124:125], v[152:153]
	v_pk_mul_f32 v[118:119], v[118:119], v[154:155]
	v_pk_mul_f32 v[120:121], v[120:121], v[156:157]
	v_pk_mul_f32 v[122:123], v[126:127], v[122:123]
	v_pk_mul_f32 v[124:125], v[128:129], v[124:125]
	v_pk_mul_f32 v[118:119], v[114:115], v[118:119]
	v_pk_mul_f32 v[120:121], v[116:117], v[120:121]
	v_mov_b32_e32 v148, v144
	v_mad_i64_i32 v[162:163], s[28:29], v148, s30, v[164:165]
	v_cvt_pk_bf16_f32 v122, v122, v123
	v_cvt_pk_bf16_f32 v123, v124, v125
	v_cvt_pk_bf16_f32 v124, v118, v119
	v_cvt_pk_bf16_f32 v125, v120, v121
	v_lshl_add_u64 v[162:163], v[162:163], 0, v[166:167]
	global_store_dwordx4 v[162:163], v[122:125], off
	v_pk_mul_f32 v[150:151], v[110:111], v[160:161]
	v_pk_mul_f32 v[152:153], v[112:113], v[160:161]
	v_pk_mul_f32 v[154:155], v[102:103], v[160:161]
	v_pk_mul_f32 v[156:157], v[104:105], v[160:161]
	v_exp_f32_e32 v150, v150
	v_exp_f32_e32 v151, v151
	v_exp_f32_e32 v152, v152
	v_exp_f32_e32 v153, v153
	v_exp_f32_e32 v154, v154
	v_exp_f32_e32 v155, v155
	v_exp_f32_e32 v156, v156
	v_exp_f32_e32 v157, v157
	v_pk_add_f32 v[150:151], v[150:151], 1.0 op_sel_hi:[1,0]
	v_pk_add_f32 v[152:153], v[152:153], 1.0 op_sel_hi:[1,0]
	v_pk_add_f32 v[154:155], v[154:155], 1.0 op_sel_hi:[1,0]
	v_pk_add_f32 v[156:157], v[156:157], 1.0 op_sel_hi:[1,0]
	v_rcp_f32_e32 v150, v150
	v_rcp_f32_e32 v151, v151
	v_rcp_f32_e32 v152, v152
	v_rcp_f32_e32 v153, v153
	v_rcp_f32_e32 v154, v154
	v_rcp_f32_e32 v155, v155
	v_rcp_f32_e32 v156, v156
	v_rcp_f32_e32 v157, v157
	v_pk_mul_f32 v[110:111], v[110:111], v[150:151]
	v_pk_mul_f32 v[112:113], v[112:113], v[152:153]
	v_pk_mul_f32 v[102:103], v[102:103], v[154:155]
	v_pk_mul_f32 v[104:105], v[104:105], v[156:157]
	v_pk_mul_f32 v[110:111], v[106:107], v[110:111]
	v_pk_mul_f32 v[112:113], v[108:109], v[112:113]
	v_pk_mul_f32 v[102:103], v[98:99], v[102:103]
	v_pk_mul_f32 v[104:105], v[100:101], v[104:105]
	v_add_u32_e32 v148, 16, v144
	v_mad_i64_i32 v[162:163], s[28:29], v148, s30, v[164:165]
	v_cvt_pk_bf16_f32 v110, v110, v111
	v_cvt_pk_bf16_f32 v111, v112, v113
	v_cvt_pk_bf16_f32 v112, v102, v103
	v_cvt_pk_bf16_f32 v113, v104, v105
	v_lshl_add_u64 v[162:163], v[162:163], 0, v[166:167]
	global_store_dwordx4 v[162:163], v[110:113], off
	v_pk_mul_f32 v[150:151], v[94:95], v[160:161]
	v_pk_mul_f32 v[152:153], v[96:97], v[160:161]
	v_pk_mul_f32 v[154:155], v[84:85], v[160:161]
	v_pk_mul_f32 v[156:157], v[86:87], v[160:161]
	v_exp_f32_e32 v150, v150
	v_exp_f32_e32 v151, v151
	v_exp_f32_e32 v152, v152
	v_exp_f32_e32 v153, v153
	v_exp_f32_e32 v154, v154
	v_exp_f32_e32 v155, v155
	v_exp_f32_e32 v156, v156
	v_exp_f32_e32 v157, v157
	v_pk_add_f32 v[150:151], v[150:151], 1.0 op_sel_hi:[1,0]
	v_pk_add_f32 v[152:153], v[152:153], 1.0 op_sel_hi:[1,0]
	v_pk_add_f32 v[154:155], v[154:155], 1.0 op_sel_hi:[1,0]
	v_pk_add_f32 v[156:157], v[156:157], 1.0 op_sel_hi:[1,0]
	v_rcp_f32_e32 v150, v150
	v_rcp_f32_e32 v151, v151
	v_rcp_f32_e32 v152, v152
	v_rcp_f32_e32 v153, v153
	v_rcp_f32_e32 v154, v154
	v_rcp_f32_e32 v155, v155
	v_rcp_f32_e32 v156, v156
	v_rcp_f32_e32 v157, v157
	v_pk_mul_f32 v[94:95], v[94:95], v[150:151]
	v_pk_mul_f32 v[96:97], v[96:97], v[152:153]
	v_pk_mul_f32 v[84:85], v[84:85], v[154:155]
	v_pk_mul_f32 v[86:87], v[86:87], v[156:157]
	v_pk_mul_f32 v[94:95], v[88:89], v[94:95]
	v_pk_mul_f32 v[96:97], v[90:91], v[96:97]
	v_pk_mul_f32 v[84:85], v[80:81], v[84:85]
	v_pk_mul_f32 v[86:87], v[82:83], v[86:87]
	v_add_u32_e32 v148, 32, v144
	v_mad_i64_i32 v[162:163], s[28:29], v148, s30, v[164:165]
	v_cvt_pk_bf16_f32 v94, v94, v95
	v_cvt_pk_bf16_f32 v95, v96, v97
	v_cvt_pk_bf16_f32 v96, v84, v85
	v_cvt_pk_bf16_f32 v97, v86, v87
	v_lshl_add_u64 v[162:163], v[162:163], 0, v[166:167]
	global_store_dwordx4 v[162:163], v[94:97], off
	v_pk_mul_f32 v[150:151], v[76:77], v[160:161]
	v_pk_mul_f32 v[152:153], v[78:79], v[160:161]
	v_pk_mul_f32 v[154:155], v[68:69], v[160:161]
	v_pk_mul_f32 v[156:157], v[70:71], v[160:161]
	v_exp_f32_e32 v150, v150
	v_exp_f32_e32 v151, v151
	v_exp_f32_e32 v152, v152
	v_exp_f32_e32 v153, v153
	v_exp_f32_e32 v154, v154
	v_exp_f32_e32 v155, v155
	v_exp_f32_e32 v156, v156
	v_exp_f32_e32 v157, v157
	v_pk_add_f32 v[150:151], v[150:151], 1.0 op_sel_hi:[1,0]
	v_pk_add_f32 v[152:153], v[152:153], 1.0 op_sel_hi:[1,0]
	v_pk_add_f32 v[154:155], v[154:155], 1.0 op_sel_hi:[1,0]
	v_pk_add_f32 v[156:157], v[156:157], 1.0 op_sel_hi:[1,0]
	v_rcp_f32_e32 v150, v150
	v_rcp_f32_e32 v151, v151
	v_rcp_f32_e32 v152, v152
	v_rcp_f32_e32 v153, v153
	v_rcp_f32_e32 v154, v154
	v_rcp_f32_e32 v155, v155
	v_rcp_f32_e32 v156, v156
	v_rcp_f32_e32 v157, v157
	v_pk_mul_f32 v[76:77], v[76:77], v[150:151]
	v_pk_mul_f32 v[78:79], v[78:79], v[152:153]
	v_pk_mul_f32 v[68:69], v[68:69], v[154:155]
	v_pk_mul_f32 v[70:71], v[70:71], v[156:157]
	v_pk_mul_f32 v[76:77], v[72:73], v[76:77]
	v_pk_mul_f32 v[78:79], v[74:75], v[78:79]
	v_pk_mul_f32 v[68:69], v[64:65], v[68:69]
	v_pk_mul_f32 v[70:71], v[66:67], v[70:71]
	v_add_u32_e32 v148, 48, v144
	v_mad_i64_i32 v[162:163], s[28:29], v148, s30, v[164:165]
	v_cvt_pk_bf16_f32 v76, v76, v77
	v_cvt_pk_bf16_f32 v77, v78, v79
	v_cvt_pk_bf16_f32 v78, v68, v69
	v_cvt_pk_bf16_f32 v79, v70, v71
	v_lshl_add_u64 v[162:163], v[162:163], 0, v[166:167]
	global_store_dwordx4 v[162:163], v[76:79], off
	v_pk_mul_f32 v[150:151], v[60:61], v[160:161]
	v_pk_mul_f32 v[152:153], v[62:63], v[160:161]
	v_pk_mul_f32 v[154:155], v[52:53], v[160:161]
	v_pk_mul_f32 v[156:157], v[54:55], v[160:161]
	v_exp_f32_e32 v150, v150
	v_exp_f32_e32 v151, v151
	v_exp_f32_e32 v152, v152
	v_exp_f32_e32 v153, v153
	v_exp_f32_e32 v154, v154
	v_exp_f32_e32 v155, v155
	v_exp_f32_e32 v156, v156
	v_exp_f32_e32 v157, v157
	v_pk_add_f32 v[150:151], v[150:151], 1.0 op_sel_hi:[1,0]
	v_pk_add_f32 v[152:153], v[152:153], 1.0 op_sel_hi:[1,0]
	v_pk_add_f32 v[154:155], v[154:155], 1.0 op_sel_hi:[1,0]
	v_pk_add_f32 v[156:157], v[156:157], 1.0 op_sel_hi:[1,0]
	v_rcp_f32_e32 v150, v150
	v_rcp_f32_e32 v151, v151
	v_rcp_f32_e32 v152, v152
	v_rcp_f32_e32 v153, v153
	v_rcp_f32_e32 v154, v154
	v_rcp_f32_e32 v155, v155
	v_rcp_f32_e32 v156, v156
	v_rcp_f32_e32 v157, v157
	v_pk_mul_f32 v[60:61], v[60:61], v[150:151]
	v_pk_mul_f32 v[62:63], v[62:63], v[152:153]
	v_pk_mul_f32 v[52:53], v[52:53], v[154:155]
	v_pk_mul_f32 v[54:55], v[54:55], v[156:157]
	v_pk_mul_f32 v[60:61], v[56:57], v[60:61]
	v_pk_mul_f32 v[62:63], v[58:59], v[62:63]
	v_pk_mul_f32 v[52:53], v[48:49], v[52:53]
	v_pk_mul_f32 v[54:55], v[50:51], v[54:55]
	v_add_u32_e32 v148, 128, v144
	v_mad_i64_i32 v[162:163], s[28:29], v148, s30, v[164:165]
	v_cvt_pk_bf16_f32 v60, v60, v61
	v_cvt_pk_bf16_f32 v61, v62, v63
	v_cvt_pk_bf16_f32 v62, v52, v53
	v_cvt_pk_bf16_f32 v63, v54, v55
	v_lshl_add_u64 v[162:163], v[162:163], 0, v[166:167]
	global_store_dwordx4 v[162:163], v[60:63], off
	v_pk_mul_f32 v[150:151], v[44:45], v[160:161]
	v_pk_mul_f32 v[152:153], v[46:47], v[160:161]
	v_pk_mul_f32 v[154:155], v[36:37], v[160:161]
	v_pk_mul_f32 v[156:157], v[38:39], v[160:161]
	v_exp_f32_e32 v150, v150
	v_exp_f32_e32 v151, v151
	v_exp_f32_e32 v152, v152
	v_exp_f32_e32 v153, v153
	v_exp_f32_e32 v154, v154
	v_exp_f32_e32 v155, v155
	v_exp_f32_e32 v156, v156
	v_exp_f32_e32 v157, v157
	v_pk_add_f32 v[150:151], v[150:151], 1.0 op_sel_hi:[1,0]
	v_pk_add_f32 v[152:153], v[152:153], 1.0 op_sel_hi:[1,0]
	v_pk_add_f32 v[154:155], v[154:155], 1.0 op_sel_hi:[1,0]
	v_pk_add_f32 v[156:157], v[156:157], 1.0 op_sel_hi:[1,0]
	v_rcp_f32_e32 v150, v150
	v_rcp_f32_e32 v151, v151
	v_rcp_f32_e32 v152, v152
	v_rcp_f32_e32 v153, v153
	v_rcp_f32_e32 v154, v154
	v_rcp_f32_e32 v155, v155
	v_rcp_f32_e32 v156, v156
	v_rcp_f32_e32 v157, v157
	v_pk_mul_f32 v[44:45], v[44:45], v[150:151]
	v_pk_mul_f32 v[46:47], v[46:47], v[152:153]
	v_pk_mul_f32 v[36:37], v[36:37], v[154:155]
	v_pk_mul_f32 v[38:39], v[38:39], v[156:157]
	v_pk_mul_f32 v[44:45], v[40:41], v[44:45]
	v_pk_mul_f32 v[46:47], v[42:43], v[46:47]
	v_pk_mul_f32 v[36:37], v[32:33], v[36:37]
	v_pk_mul_f32 v[38:39], v[34:35], v[38:39]
	v_add_u32_e32 v148, 144, v144
	v_mad_i64_i32 v[162:163], s[28:29], v148, s30, v[164:165]
	v_cvt_pk_bf16_f32 v44, v44, v45
	v_cvt_pk_bf16_f32 v45, v46, v47
	v_cvt_pk_bf16_f32 v46, v36, v37
	v_cvt_pk_bf16_f32 v47, v38, v39
	v_lshl_add_u64 v[162:163], v[162:163], 0, v[166:167]
	global_store_dwordx4 v[162:163], v[44:47], off
	v_pk_mul_f32 v[150:151], v[28:29], v[160:161]
	v_pk_mul_f32 v[152:153], v[30:31], v[160:161]
	v_pk_mul_f32 v[154:155], v[20:21], v[160:161]
	v_pk_mul_f32 v[156:157], v[22:23], v[160:161]
	v_exp_f32_e32 v150, v150
	v_exp_f32_e32 v151, v151
	v_exp_f32_e32 v152, v152
	v_exp_f32_e32 v153, v153
	v_exp_f32_e32 v154, v154
	v_exp_f32_e32 v155, v155
	v_exp_f32_e32 v156, v156
	v_exp_f32_e32 v157, v157
	v_pk_add_f32 v[150:151], v[150:151], 1.0 op_sel_hi:[1,0]
	v_pk_add_f32 v[152:153], v[152:153], 1.0 op_sel_hi:[1,0]
	v_pk_add_f32 v[154:155], v[154:155], 1.0 op_sel_hi:[1,0]
	v_pk_add_f32 v[156:157], v[156:157], 1.0 op_sel_hi:[1,0]
	v_rcp_f32_e32 v150, v150
	v_rcp_f32_e32 v151, v151
	v_rcp_f32_e32 v152, v152
	v_rcp_f32_e32 v153, v153
	v_rcp_f32_e32 v154, v154
	v_rcp_f32_e32 v155, v155
	v_rcp_f32_e32 v156, v156
	v_rcp_f32_e32 v157, v157
	v_pk_mul_f32 v[28:29], v[28:29], v[150:151]
	v_pk_mul_f32 v[30:31], v[30:31], v[152:153]
	v_pk_mul_f32 v[20:21], v[20:21], v[154:155]
	v_pk_mul_f32 v[22:23], v[22:23], v[156:157]
	v_pk_mul_f32 v[28:29], v[24:25], v[28:29]
	v_pk_mul_f32 v[30:31], v[26:27], v[30:31]
	v_pk_mul_f32 v[20:21], v[16:17], v[20:21]
	v_pk_mul_f32 v[22:23], v[18:19], v[22:23]
	v_add_u32_e32 v148, 160, v144
	v_mad_i64_i32 v[162:163], s[28:29], v148, s30, v[164:165]
	v_cvt_pk_bf16_f32 v28, v28, v29
	v_cvt_pk_bf16_f32 v29, v30, v31
	v_cvt_pk_bf16_f32 v30, v20, v21
	v_cvt_pk_bf16_f32 v31, v22, v23
	v_lshl_add_u64 v[162:163], v[162:163], 0, v[166:167]
	global_store_dwordx4 v[162:163], v[28:31], off
	v_pk_mul_f32 v[150:151], v[12:13], v[160:161]
	v_pk_mul_f32 v[152:153], v[14:15], v[160:161]
	v_pk_mul_f32 v[154:155], v[4:5], v[160:161]
	v_pk_mul_f32 v[156:157], v[6:7], v[160:161]
	v_exp_f32_e32 v150, v150
	v_exp_f32_e32 v151, v151
	v_exp_f32_e32 v152, v152
	v_exp_f32_e32 v153, v153
	v_exp_f32_e32 v154, v154
	v_exp_f32_e32 v155, v155
	v_exp_f32_e32 v156, v156
	v_exp_f32_e32 v157, v157
	v_pk_add_f32 v[150:151], v[150:151], 1.0 op_sel_hi:[1,0]
	v_pk_add_f32 v[152:153], v[152:153], 1.0 op_sel_hi:[1,0]
	v_pk_add_f32 v[154:155], v[154:155], 1.0 op_sel_hi:[1,0]
	v_pk_add_f32 v[156:157], v[156:157], 1.0 op_sel_hi:[1,0]
	v_rcp_f32_e32 v150, v150
	v_rcp_f32_e32 v151, v151
	v_rcp_f32_e32 v152, v152
	v_rcp_f32_e32 v153, v153
	v_rcp_f32_e32 v154, v154
	v_rcp_f32_e32 v155, v155
	v_rcp_f32_e32 v156, v156
	v_rcp_f32_e32 v157, v157
	v_pk_mul_f32 v[12:13], v[12:13], v[150:151]
	v_pk_mul_f32 v[14:15], v[14:15], v[152:153]
	v_pk_mul_f32 v[4:5], v[4:5], v[154:155]
	v_pk_mul_f32 v[6:7], v[6:7], v[156:157]
	v_pk_mul_f32 v[12:13], v[8:9], v[12:13]
	v_pk_mul_f32 v[14:15], v[10:11], v[14:15]
	v_pk_mul_f32 v[4:5], v[0:1], v[4:5]
	v_pk_mul_f32 v[6:7], v[2:3], v[6:7]
	v_add_u32_e32 v148, 176, v144
	v_mad_i64_i32 v[162:163], s[28:29], v148, s30, v[164:165]
	v_cvt_pk_bf16_f32 v12, v12, v13
	v_cvt_pk_bf16_f32 v13, v14, v15
	v_cvt_pk_bf16_f32 v14, v4, v5
	v_cvt_pk_bf16_f32 v15, v6, v7
	v_lshl_add_u64 v[162:163], v[162:163], 0, v[166:167]
	global_store_dwordx4 v[162:163], v[12:15], off
	s_mov_b64 s[28:29], -1
	s_cbranch_vccnz .LBB0_498
	s_andn2_b64 vcc, exec, s[18:19]
	s_cbranch_vccnz .LBB0_497
	s_barrier
	s_branch .LBB0_497

.LBB0_1094:
	s_waitcnt vmcnt(0)
	global_load_dword v240, v[120:121], off offset:8
	global_load_dword v241, v[122:123], off offset:8
	global_load_dwordx4 v[232:235], v[118:119], off
	global_load_dwordx4 v[236:239], v[116:117], off
	global_load_dwordx4 v[36:39], v[118:119], off offset:64
	global_load_dwordx4 v[32:35], v[116:117], off offset:64
	s_mov_b32 s4, s7
	s_waitcnt vmcnt(5)
	v_div_scale_f32 v27, s[0:1], v24, v24, v240
	v_rcp_f32_e32 v28, v27
	s_nop 0
	v_fma_f32 v29, -v27, v28, 1.0
	v_fmac_f32_e32 v28, v29, v28
	v_div_scale_f32 v29, vcc, v240, v24, v240
	v_mul_f32_e32 v30, v29, v28
	v_fma_f32 v31, -v27, v30, v29
	v_fmac_f32_e32 v30, v31, v28
	v_fma_f32 v27, -v27, v30, v29
	v_div_fmas_f32 v27, v27, v28, v30
	v_div_fixup_f32 v24, v27, v24, v240
	s_waitcnt vmcnt(4)
	v_div_scale_f32 v27, s[0:1], v25, v25, v241
	v_rcp_f32_e32 v28, v27
	s_nop 0
	v_fma_f32 v29, -v27, v28, 1.0
	v_fmac_f32_e32 v28, v29, v28
	v_div_scale_f32 v29, vcc, v241, v25, v241
	v_mul_f32_e32 v30, v29, v28
	v_fma_f32 v31, -v27, v30, v29
	v_fmac_f32_e32 v30, v31, v28
	v_fma_f32 v27, -v27, v30, v29
	v_div_fmas_f32 v27, v27, v28, v30
	v_div_fixup_f32 v30, v27, v25, v241
	v_readlane_b32 s0, v250, 35
	v_readlane_b32 s1, v250, 36
	v_add_lshl_u32 v92, v218, v148, 1
	v_lshlrev_b64 v[28:29], 11, v[156:157]
	v_lshlrev_b64 v[26:27], 11, v[160:161]
	v_lshl_add_u64 v[28:29], s[0:1], 0, v[28:29]
	v_lshl_add_u64 v[26:27], s[0:1], 0, v[26:27]
	v_lshl_add_u64 v[28:29], v[28:29], 0, v[92:93]
	v_lshl_add_u64 v[26:27], v[26:27], 0, v[92:93]
	s_waitcnt vmcnt(3)
	v_pk_fma_f32 v[46:47], v[46:47], v[24:25], v[234:235] op_sel_hi:[1,0,1]
	v_pk_fma_f32 v[44:45], v[44:45], v[24:25], v[232:233] op_sel_hi:[1,0,1]
	v_cvt_pk_bf16_f32 v44, v44, v45
	v_cvt_pk_bf16_f32 v45, v46, v47
	global_store_dwordx2 v[28:29], v[44:45], off
	global_load_dwordx4 v[232:235], v[118:119], off offset:128
	s_waitcnt vmcnt(4)
	v_pk_fma_f32 v[42:43], v[42:43], v[30:31], v[238:239] op_sel_hi:[1,0,1]
	v_pk_fma_f32 v[40:41], v[40:41], v[30:31], v[236:237] op_sel_hi:[1,0,1]
	v_cvt_pk_bf16_f32 v40, v40, v41
	v_cvt_pk_bf16_f32 v41, v42, v43
	global_store_dwordx2 v[26:27], v[40:41], off
	global_load_dwordx4 v[236:239], v[116:117], off offset:128
	s_waitcnt vmcnt(5)
	v_pk_fma_f32 v[22:23], v[22:23], v[24:25], v[38:39] op_sel_hi:[1,0,1]
	v_pk_fma_f32 v[20:21], v[20:21], v[24:25], v[36:37] op_sel_hi:[1,0,1]
	v_cvt_pk_bf16_f32 v20, v20, v21
	v_cvt_pk_bf16_f32 v21, v22, v23
	global_store_dwordx2 v[28:29], v[20:21], off offset:32
	global_load_dwordx4 v[36:39], v[118:119], off offset:192
	s_waitcnt vmcnt(6)
	v_pk_fma_f32 v[18:19], v[18:19], v[30:31], v[34:35] op_sel_hi:[1,0,1]
	v_pk_fma_f32 v[16:17], v[16:17], v[30:31], v[32:33] op_sel_hi:[1,0,1]
	v_cvt_pk_bf16_f32 v16, v16, v17
	v_cvt_pk_bf16_f32 v17, v18, v19
	global_store_dwordx2 v[26:27], v[16:17], off offset:32
	global_load_dwordx4 v[32:35], v[116:117], off offset:192
	s_waitcnt vmcnt(6)
	v_pk_fma_f32 v[14:15], v[14:15], v[24:25], v[234:235] op_sel_hi:[1,0,1]
	v_pk_fma_f32 v[12:13], v[12:13], v[24:25], v[232:233] op_sel_hi:[1,0,1]
	v_cvt_pk_bf16_f32 v12, v12, v13
	v_cvt_pk_bf16_f32 v13, v14, v15
	global_store_dwordx2 v[28:29], v[12:13], off offset:64
	s_waitcnt vmcnt(5)
	v_pk_fma_f32 v[10:11], v[10:11], v[30:31], v[238:239] op_sel_hi:[1,0,1]
	v_pk_fma_f32 v[8:9], v[8:9], v[30:31], v[236:237] op_sel_hi:[1,0,1]
	v_cvt_pk_bf16_f32 v8, v8, v9
	v_cvt_pk_bf16_f32 v9, v10, v11
	global_store_dwordx2 v[26:27], v[8:9], off offset:64
	s_waitcnt vmcnt(4)
	v_pk_fma_f32 v[6:7], v[6:7], v[24:25], v[38:39] op_sel_hi:[1,0,1]
	v_pk_fma_f32 v[4:5], v[4:5], v[24:25], v[36:37] op_sel_hi:[1,0,1]
	v_cvt_pk_bf16_f32 v4, v4, v5
	v_cvt_pk_bf16_f32 v5, v6, v7
	global_store_dwordx2 v[28:29], v[4:5], off offset:96
	s_waitcnt vmcnt(3)
	v_pk_fma_f32 v[2:3], v[2:3], v[30:31], v[34:35] op_sel_hi:[1,0,1]
	v_pk_fma_f32 v[0:1], v[0:1], v[30:31], v[32:33] op_sel_hi:[1,0,1]
	v_cvt_pk_bf16_f32 v0, v0, v1
	v_cvt_pk_bf16_f32 v1, v2, v3
	global_store_dwordx2 v[26:27], v[0:1], off offset:96
	s_waitcnt lgkmcnt(0)
	s_barrier

.LBB0_1385:
	s_waitcnt vmcnt(0)
	v_readlane_b32 s2, v250, 23
	v_readlane_b32 s3, v250, 24
	v_mov_b32_e32 v163, v93
	v_mov_b32_e32 v95, v93
	v_lshlrev_b32_e32 v92, 2, v148
	v_lshl_add_u64 v[36:37], s[2:3], 0, v[170:171]
	v_lshl_add_u64 v[120:121], v[36:37], 0, v[162:163]
	v_lshl_add_u64 v[36:37], s[2:3], 0, v[168:169]
	v_lshl_add_u64 v[122:123], v[36:37], 0, v[162:163]
	global_load_dword v240, v[120:121], off offset:4
	global_load_dword v241, v[122:123], off offset:4
	v_readlane_b32 s2, v250, 25
	v_readlane_b32 s3, v250, 26
	s_nop 1
	v_lshl_add_u64 v[36:37], s[2:3], 0, v[164:165]
	v_lshl_add_u64 v[36:37], v[36:37], 0, v[94:95]
	v_lshl_add_u64 v[118:119], v[36:37], 0, v[92:93]
	v_lshl_add_u64 v[36:37], s[2:3], 0, v[166:167]
	v_lshl_add_u64 v[36:37], v[36:37], 0, v[94:95]
	v_lshl_add_u64 v[116:117], v[36:37], 0, v[92:93]
	global_load_dwordx4 v[232:235], v[118:119], off
	global_load_dwordx4 v[236:239], v[116:117], off
	s_waitcnt vmcnt(3)
	v_div_scale_f32 v35, s[0:1], v32, v32, v240
	v_rcp_f32_e32 v36, v35
	s_nop 0
	v_fma_f32 v37, -v35, v36, 1.0
	v_fmac_f32_e32 v36, v37, v36
	v_div_scale_f32 v37, vcc, v240, v32, v240
	v_mul_f32_e32 v38, v37, v36
	v_fma_f32 v39, -v35, v38, v37
	v_fmac_f32_e32 v38, v39, v36
	v_fma_f32 v35, -v35, v38, v37
	v_div_fmas_f32 v35, v35, v36, v38
	v_div_fixup_f32 v32, v35, v32, v240
	s_waitcnt vmcnt(2)
	v_div_scale_f32 v35, s[0:1], v33, v33, v241
	v_rcp_f32_e32 v36, v35
	s_nop 0
	v_fma_f32 v37, -v35, v36, 1.0
	v_fmac_f32_e32 v36, v37, v36
	v_div_scale_f32 v37, vcc, v241, v33, v241
	v_mul_f32_e32 v38, v37, v36
	v_fma_f32 v39, -v35, v38, v37
	v_fmac_f32_e32 v38, v39, v36
	v_fma_f32 v35, -v35, v38, v37
	v_div_fmas_f32 v35, v35, v36, v38
	v_div_fixup_f32 v34, v35, v33, v241
	global_load_dwordx4 v[36:39], v[118:119], off offset:64
	s_sub_i32 s0, 0x5e1, s92
	s_max_i32 s0, s0, 0
	s_ashr_i32 s1, s95, 6
	s_lshr_b32 s0, s0, 6
	s_lshl_b32 s1, 2, s1
	s_add_i32 s1, s1, -1
	s_lshl_b32 s0, -1, s0
	s_and_b32 s0, s1, s0
	s_cmp_eq_u32 s0, 0
	s_waitcnt vmcnt(2)
	v_pk_fma_f32 v[18:19], v[18:19], v[32:33], v[234:235] op_sel_hi:[1,0,1]
	v_pk_fma_f32 v[16:17], v[16:17], v[32:33], v[232:233] op_sel_hi:[1,0,1]
	global_store_dwordx4 v[118:119], v[16:19], off
	global_load_dwordx4 v[232:235], v[116:117], off offset:64
	s_waitcnt vmcnt(3)
	v_pk_fma_f32 v[2:3], v[2:3], v[34:35], v[238:239] op_sel_hi:[1,0,1]
	v_pk_fma_f32 v[0:1], v[0:1], v[34:35], v[236:237] op_sel_hi:[1,0,1]
	global_store_dwordx4 v[116:117], v[0:3], off
	global_load_dwordx4 v[236:239], v[118:119], off offset:128
	s_waitcnt vmcnt(4)
	v_pk_fma_f32 v[22:23], v[22:23], v[32:33], v[38:39] op_sel_hi:[1,0,1]
	v_pk_fma_f32 v[20:21], v[20:21], v[32:33], v[36:37] op_sel_hi:[1,0,1]
	global_store_dwordx4 v[118:119], v[20:23], off offset:64
	global_load_dwordx4 v[36:39], v[116:117], off offset:128
	s_waitcnt vmcnt(4)
	v_pk_fma_f32 v[6:7], v[6:7], v[34:35], v[234:235] op_sel_hi:[1,0,1]
	v_pk_fma_f32 v[4:5], v[4:5], v[34:35], v[232:233] op_sel_hi:[1,0,1]
	global_store_dwordx4 v[116:117], v[4:7], off offset:64
	global_load_dwordx4 v[232:235], v[118:119], off offset:192
	s_waitcnt vmcnt(4)
	v_pk_fma_f32 v[26:27], v[26:27], v[32:33], v[238:239] op_sel_hi:[1,0,1]
	v_pk_fma_f32 v[24:25], v[24:25], v[32:33], v[236:237] op_sel_hi:[1,0,1]
	global_store_dwordx4 v[118:119], v[24:27], off offset:128
	global_load_dwordx4 v[236:239], v[116:117], off offset:192
	s_waitcnt vmcnt(4)
	v_pk_fma_f32 v[10:11], v[10:11], v[34:35], v[38:39] op_sel_hi:[1,0,1]
	v_pk_fma_f32 v[8:9], v[8:9], v[34:35], v[36:37] op_sel_hi:[1,0,1]
	global_store_dwordx4 v[116:117], v[8:11], off offset:128
	s_waitcnt vmcnt(3)
	v_pk_fma_f32 v[30:31], v[30:31], v[32:33], v[234:235] op_sel_hi:[1,0,1]
	v_pk_fma_f32 v[28:29], v[28:29], v[32:33], v[232:233] op_sel_hi:[1,0,1]
	global_store_dwordx4 v[118:119], v[28:31], off offset:192
	s_waitcnt vmcnt(2)
	v_pk_fma_f32 v[14:15], v[14:15], v[34:35], v[238:239] op_sel_hi:[1,0,1]
	v_pk_fma_f32 v[12:13], v[12:13], v[34:35], v[236:237] op_sel_hi:[1,0,1]
	global_store_dwordx4 v[116:117], v[12:15], off offset:192
	s_nop 1
	v_mov_b32_e32 v0, v196
	s_cbranch_scc1 .LBB0_1442
	s_lshl_b32 s1, s79, 1
	v_readlane_b32 s2, v250, 31
	s_add_u32 s2, s2, s1
	v_readlane_b32 s3, v250, 32
	v_ashrrev_i32_e32 v124, 3, v0
	s_ff1_i32_b32 s14, s0
	s_addc_u32 s3, s3, 0
	v_readlane_b32 s4, v250, 33
	v_lshl_add_u32 v2, s14, 6, v124
	v_lshlrev_b32_e32 v0, 3, v0
	s_add_u32 s4, s4, s1
	v_readlane_b32 s1, v250, 34
	v_ashrrev_i32_e32 v3, 31, v2
	v_and_b32_e32 v0, 56, v0
	v_ashrrev_i32_e32 v125, 31, v124
	s_addc_u32 s5, s1, 0
	v_lshlrev_b64 v[2:3], 7, v[2:3]
	v_lshlrev_b32_e32 v92, 1, v0
	v_lshlrev_b64 v[0:1], 12, v[124:125]
	v_lshl_add_u64 v[2:3], s[2:3], 0, v[2:3]
	v_lshl_add_u64 v[0:1], s[4:5], 0, v[0:1]
	s_lshl_b32 s96, s14, 7
	v_lshl_add_u64 v[2:3], v[2:3], 0, v[92:93]
	v_lshl_add_u64 v[4:5], v[0:1], 0, s[96:97]
	v_lshl_add_u64 v[4:5], v[4:5], 0, v[92:93]
	global_load_dwordx4 v[24:27], v[2:3], off
	global_load_dwordx4 v[28:31], v[4:5], off
	s_add_i32 s1, s0, -1
	s_and_b32 s0, s1, s0
	v_sub_co_u32_e64 v2, s[74:75], s0, 1
	s_nop 0
	v_readfirstlane_b32 s4, v2
	s_ff1_i32_b32 s1, s0
	s_and_b64 vcc, exec, s[74:75]
	s_cbranch_vccnz .LBB0_1388
	v_lshl_add_u32 v2, s1, 6, v124
	v_ashrrev_i32_e32 v3, 31, v2
	v_lshlrev_b64 v[2:3], 7, v[2:3]
	v_lshl_add_u64 v[2:3], s[2:3], 0, v[2:3]
	s_lshl_b32 s96, s1, 7
	v_lshl_add_u64 v[2:3], v[2:3], 0, v[92:93]
	v_lshl_add_u64 v[4:5], v[0:1], 0, s[96:97]
	v_lshl_add_u64 v[4:5], v[4:5], 0, v[92:93]
	global_load_dwordx4 v[32:35], v[2:3], off
	global_load_dwordx4 v[36:39], v[4:5], off
